# static s_setprio 1 for waves 4-7 inside the MLA and SWA tile loops
# baseline (speedup 1.0000x reference)
.LBB0_561:
	s_waitcnt lgkmcnt(0)
	s_barrier
	s_cmp_lt_u32 s3, 4
	s_cbranch_scc1 .Lmla_prio_done
	s_setprio 1

.Lmla_noresc_t:
	s_waitcnt vmcnt(0) lgkmcnt(0)
	s_barrier
	ds_read_b64_tr_b16 v[214:215], v184
	ds_read_b64_tr_b16 v[216:217], v184 offset:2048
	ds_read_b64_tr_b16 v[218:219], v184 offset:4096
	ds_read_b64_tr_b16 v[220:221], v184 offset:6144
	ds_read_b64_tr_b16 v[222:223], v184 offset:8192
	ds_read_b64_tr_b16 v[224:225], v184 offset:10240
	ds_read_b64_tr_b16 v[226:227], v184 offset:12288
	ds_read_b64_tr_b16 v[228:229], v184 offset:14336
	v_exp_f32_e32 v64, v64
	v_exp_f32_e32 v65, v65
	v_add_f32_e32 v212, v64, v212
	v_exp_f32_e32 v66, v66
	v_add_f32_e32 v212, v65, v212
	v_exp_f32_e32 v67, v67
	v_add_f32_e32 v212, v66, v212
	v_exp_f32_e32 v68, v68
	v_add_f32_e32 v212, v67, v212
	v_exp_f32_e32 v69, v69
	v_add_f32_e32 v212, v68, v212
	v_exp_f32_e32 v70, v70
	v_add_f32_e32 v212, v69, v212
	v_exp_f32_e32 v71, v71
	v_add_f32_e32 v212, v70, v212
	v_exp_f32_e32 v72, v72
	v_add_f32_e32 v212, v71, v212
	v_exp_f32_e32 v73, v73
	v_add_f32_e32 v212, v72, v212
	v_exp_f32_e32 v74, v74
	v_add_f32_e32 v212, v73, v212
	v_exp_f32_e32 v75, v75
	v_add_f32_e32 v212, v74, v212
	v_exp_f32_e32 v76, v76
	v_add_f32_e32 v212, v75, v212
	v_exp_f32_e32 v77, v77
	v_add_f32_e32 v212, v76, v212
	v_exp_f32_e32 v78, v78
	v_add_f32_e32 v212, v77, v212
	v_exp_f32_e32 v79, v79
	v_add_f32_e32 v212, v78, v212
	v_add_f32_e32 v212, v79, v212
	v_mov_b32_e32 v213, v212
	v_cvt_pk_bf16_f32 v152, v64, v65
	v_cvt_pk_bf16_f32 v153, v66, v67
	v_cvt_pk_bf16_f32 v154, v68, v69
	v_cvt_pk_bf16_f32 v155, v70, v71
	v_cvt_pk_bf16_f32 v156, v72, v73
	v_cvt_pk_bf16_f32 v157, v74, v75
	v_cvt_pk_bf16_f32 v158, v76, v77
	v_cvt_pk_bf16_f32 v159, v78, v79
	v_permlane32_swap_b32_e32 v212, v213
	v_add_f32_e32 v252, v212, v213
	v_fma_f32 v183, v207, v183, v252
	v_permlane32_swap_b32_e32 v152, v154
	v_permlane32_swap_b32_e32 v153, v155
	v_permlane32_swap_b32_e32 v156, v158
	v_permlane32_swap_b32_e32 v157, v159
	s_waitcnt lgkmcnt(6)
	v_mfma_f32_32x32x16_bf16 v[0:15], v[144:147], v[214:217], v[0:15]
	ds_read_b64_tr_b16 v[214:215], v184 offset:512
	ds_read_b64_tr_b16 v[216:217], v184 offset:2560
	s_waitcnt lgkmcnt(6)
	v_mfma_f32_32x32x16_bf16 v[0:15], v[148:151], v[218:221], v[0:15]
	ds_read_b64_tr_b16 v[218:219], v184 offset:4608
	ds_read_b64_tr_b16 v[220:221], v184 offset:6656
	s_waitcnt lgkmcnt(6)
	v_mfma_f32_32x32x16_bf16 v[0:15], v[152:155], v[222:225], v[0:15]
	ds_read_b64_tr_b16 v[222:223], v184 offset:8704
	ds_read_b64_tr_b16 v[224:225], v184 offset:10752
	s_waitcnt lgkmcnt(6)
	v_mfma_f32_32x32x16_bf16 v[0:15], v[156:159], v[226:229], v[0:15]
	ds_read_b64_tr_b16 v[226:227], v184 offset:12800
	ds_read_b64_tr_b16 v[228:229], v184 offset:14848
	s_waitcnt lgkmcnt(6)
	v_mfma_f32_32x32x16_bf16 v[48:63], v[144:147], v[214:217], v[48:63]
	ds_read_b64_tr_b16 v[214:215], v184 offset:1024
	ds_read_b64_tr_b16 v[216:217], v184 offset:3072
	s_waitcnt lgkmcnt(6)
	v_mfma_f32_32x32x16_bf16 v[48:63], v[148:151], v[218:221], v[48:63]
	ds_read_b64_tr_b16 v[218:219], v184 offset:5120
	ds_read_b64_tr_b16 v[220:221], v184 offset:7168
	s_waitcnt lgkmcnt(6)
	v_mfma_f32_32x32x16_bf16 v[48:63], v[152:155], v[222:225], v[48:63]
	ds_read_b64_tr_b16 v[222:223], v184 offset:9216
	ds_read_b64_tr_b16 v[224:225], v184 offset:11264
	s_waitcnt lgkmcnt(6)
	v_mfma_f32_32x32x16_bf16 v[48:63], v[156:159], v[226:229], v[48:63]
	ds_read_b64_tr_b16 v[226:227], v184 offset:13312
	ds_read_b64_tr_b16 v[228:229], v184 offset:15360
	s_waitcnt lgkmcnt(6)
	v_mfma_f32_32x32x16_bf16 v[32:47], v[144:147], v[214:217], v[32:47]
	ds_read_b64_tr_b16 v[214:215], v184 offset:1536
	ds_read_b64_tr_b16 v[216:217], v184 offset:3584
	s_waitcnt lgkmcnt(6)
	v_mfma_f32_32x32x16_bf16 v[32:47], v[148:151], v[218:221], v[32:47]
	ds_read_b64_tr_b16 v[218:219], v184 offset:5632
	ds_read_b64_tr_b16 v[220:221], v184 offset:7680
	s_waitcnt lgkmcnt(6)
	v_mfma_f32_32x32x16_bf16 v[32:47], v[152:155], v[222:225], v[32:47]
	ds_read_b64_tr_b16 v[222:223], v184 offset:9728
	ds_read_b64_tr_b16 v[224:225], v184 offset:11776
	s_waitcnt lgkmcnt(6)
	v_mfma_f32_32x32x16_bf16 v[32:47], v[156:159], v[226:229], v[32:47]
	ds_read_b64_tr_b16 v[226:227], v184 offset:13824
	ds_read_b64_tr_b16 v[228:229], v184 offset:15872
	s_waitcnt lgkmcnt(6)
	v_mfma_f32_32x32x16_bf16 v[16:31], v[144:147], v[214:217], v[16:31]
	s_waitcnt lgkmcnt(4)
	v_mfma_f32_32x32x16_bf16 v[16:31], v[148:151], v[218:221], v[16:31]
	s_waitcnt lgkmcnt(2)
	v_mfma_f32_32x32x16_bf16 v[16:31], v[152:155], v[222:225], v[16:31]
	s_waitcnt lgkmcnt(0)
	v_mfma_f32_32x32x16_bf16 v[16:31], v[156:159], v[226:229], v[16:31]
	s_setprio 0
	s_and_saveexec_b64 s[0:1], s[8:9]
	s_cbranch_execz .LBB0_550
	ds_write_b32 v182, v183
	s_branch .LBB0_550

.LBB0_741:
	s_cmp_lt_u32 s3, 4
	s_cbranch_scc1 .Lswa_prio_done
	s_setprio 1

.Lswa_done:
	s_setprio 0
	v_mul_f32_e32 v156, 0x3fb8aa3b, v96
	v_mul_f32_e32 v157, 0x3e38aa3b, v115
	v_sub_f32_e32 v156, v156, v157
	v_exp_f32_e32 v156, v156
	v_cmp_gt_u32_e32 vcc, 32, v105
	s_nop 0
	v_add_f32_e32 v156, v156, v108
	s_nop 3
	s_and_saveexec_b64 s[0:1], vcc
	s_cbranch_execz .LBB0_730
	ds_write_b32 v107, v156 offset:32768
	s_branch .LBB0_730
